# stack18: prep and SSD-out tile fills de-serialised (all loads in flight, counted waits) and SSD intra-chunk decay/mask done with 8 unconditional ds_read_b128 + v_cndmask instead of 32 predicated LDS r
# baseline (speedup 1.0000x reference)
; DI float bf2f(unsigned h) { return __uint_as_float(h << 16); }
; DI unsigned short f2bf(float f) { return (unsigned short)(pg8::cvt_pk_bf16(f, 0.f) & 0xffffu); }
; DI void prep_unit(const Params& P, int layer, int b, int c, char* lds, int tid) {
;     ...
;     for (int g = 0; g < 2; ++g) {
; #pragma unroll
;         for (int i = 0; i < 4; ++i) { const int q = tid + 512 * i, l = q & 127, n0 = (q >> 7) * 8;
;             const u32x4 v = *(const u32x4*)(SSDB + (size_t)(R0 + l) * 768 + 256 + 128 * g + n0);
;             bf16_t* d = BT + n0 * SP + l;
;             d[0] = (bf16_t)(v.x & 0xffffu); d[SP] = (bf16_t)(v.x >> 16); d[2 * SP] = (bf16_t)(v.y & 0xffffu); d[3 * SP] = (bf16_t)(v.y >> 16);
;             d[4 * SP] = (bf16_t)(v.z & 0xffffu); d[5 * SP] = (bf16_t)(v.z >> 16); d[6 * SP] = (bf16_t)(v.w & 0xffffu); d[7 * SP] = (bf16_t)(v.w >> 16); }
; #pragma unroll
;         for (int hs = 0; hs < 2; ++hs) { const int h = 2 * g + hs;
; #pragma unroll
;             for (int i = 0; i < 2; ++i) { const int q = tid + 512 * i, l = q & 127, p0 = (q >> 7) * 8;
;                 const u32x4 v = *(const u32x4*)(SSDB + (size_t)(R0 + l) * 768 + 64 * h + p0);
;                 const float f = dtl[h * CH + l] * expf(acs[h * CH + CH - 1] - acs[h * CH + l]);
;                 bf16_t* d = XT[hs] + p0 * SP + l;
;                 d[0] = f2bf(bf2f(v.x & 0xffffu) * f); d[SP] = f2bf(bf2f(v.x >> 16) * f); d[2 * SP] = f2bf(bf2f(v.y & 0xffffu) * f); d[3 * SP] = f2bf(bf2f(v.y >> 16) * f);
;                 d[4 * SP] = f2bf(bf2f(v.z & 0xffffu) * f); d[5 * SP] = f2bf(bf2f(v.z >> 16) * f); d[6 * SP] = f2bf(bf2f(v.w & 0xffffu) * f); d[7 * SP] = f2bf(bf2f(v.w >> 16) * f); } }
.LBB0_201:
	s_lshl_b32 s62, s5, 8
	v_lshl_add_u64 v[6:7], v[18:19], 0, s[62:63]
	v_lshl_add_u64 v[8:9], v[6:7], 0, v[82:83]
	s_lshl_b32 s100, s5, 1
	s_or_b32 s100, s100, 1
	s_lshl_b32 s100, s100, 7
	s_mov_b32 s101, s63
	v_lshl_add_u64 v[14:15], v[6:7], 0, v[84:85]
	global_load_dwordx4 v[224:227], v[8:9], off offset:512
	global_load_dwordx4 v[228:231], v[14:15], off offset:512
	v_lshl_add_u64 v[16:17], v[42:43], 1, v[6:7]
	global_load_dwordx4 v[232:235], v[16:17], off offset:512
	v_lshl_add_u64 v[16:17], v[44:45], 1, v[6:7]
	global_load_dwordx4 v[244:247], v[16:17], off offset:512
	global_load_dwordx4 v[248:251], v[8:9], off
	global_load_dwordx4 v[252:255], v[14:15], off
	v_lshl_add_u64 v[16:17], v[18:19], 0, s[100:101]
	v_lshl_add_u64 v[14:15], v[16:17], 0, v[82:83]
	global_load_dwordx4 v[90:93], v[14:15], off
	v_lshl_add_u64 v[14:15], v[16:17], 0, v[84:85]
	global_load_dwordx4 v[94:97], v[14:15], off
	v_add_u32_e32 v10, v160, v162
	v_add_u32_e32 v12, v160, v163
	s_lshl_b32 s2, s5, 10
	s_lshl_b32 s4, s5, 1
	v_add_u32_e32 v122, s4, v20
	v_ashrrev_i32_e32 v123, 31, v122
	s_waitcnt vmcnt(7)
	v_mov_b64_e32 v[2:3], v[224:225]
	v_mov_b64_e32 v[4:5], v[226:227]
	ds_write_b16 v10, v2 offset:34816
	ds_write_b16_d16_hi v10, v2 offset:35088
	ds_write_b16 v10, v3 offset:35360
	ds_write_b16_d16_hi v10, v3 offset:35632
	ds_write_b16 v10, v4 offset:35904
	ds_write_b16_d16_hi v10, v4 offset:36176
	ds_write_b16 v10, v5 offset:36448
	ds_write_b16_d16_hi v10, v5 offset:36720
	v_lshl_add_u64 v[10:11], v[6:7], 0, v[84:85]
	s_waitcnt vmcnt(6)
	v_mov_b64_e32 v[2:3], v[228:229]
	v_mov_b64_e32 v[4:5], v[230:231]
	ds_write_b16 v12, v2 offset:34816
	ds_write_b16_d16_hi v12, v2 offset:35088
	ds_write_b16 v12, v3 offset:35360
	ds_write_b16_d16_hi v12, v3 offset:35632
	ds_write_b16 v12, v4 offset:35904
	ds_write_b16_d16_hi v12, v4 offset:36176
	ds_write_b16 v12, v5 offset:36448
	ds_write_b16_d16_hi v12, v5 offset:36720
	v_lshl_add_u64 v[2:3], v[42:43], 1, v[6:7]
	s_waitcnt vmcnt(5)
	v_mov_b64_e32 v[2:3], v[232:233]
	v_mov_b64_e32 v[4:5], v[234:235]
	ds_write_b16 v29, v2 offset:34816
	ds_write_b16_d16_hi v29, v2 offset:35088
	ds_write_b16 v29, v3 offset:35360
	ds_write_b16_d16_hi v29, v3 offset:35632
	ds_write_b16 v29, v4 offset:35904
	ds_write_b16_d16_hi v29, v4 offset:36176
	ds_write_b16 v29, v5 offset:36448
	ds_write_b16_d16_hi v29, v5 offset:36720
	v_lshl_add_u64 v[2:3], v[44:45], 1, v[6:7]
	v_lshlrev_b32_e32 v6, 2, v159
	s_waitcnt vmcnt(4)
	v_mov_b64_e32 v[2:3], v[244:245]
	v_mov_b64_e32 v[4:5], v[246:247]
	ds_write_b16 v172, v2 offset:34816
	ds_write_b16_d16_hi v172, v2 offset:35088
	ds_write_b16 v172, v3 offset:35360
	ds_write_b16_d16_hi v172, v3 offset:35632
	ds_write_b16 v172, v4 offset:35904
	ds_write_b16_d16_hi v172, v4 offset:36176
	ds_write_b16 v172, v5 offset:36448
	ds_write_b16_d16_hi v172, v5 offset:36720
	v_or_b32_e32 v2, s2, v6
	v_add_u32_e32 v7, s19, v2
	v_add_u32_e32 v12, s20, v2
	s_add_i32 s2, s20, s2
	v_mov_b32_e32 v9, s2
	ds_read_b32 v8, v7
	ds_read_b32 v13, v9 offset:508
	ds_read_b32 v14, v12
	s_or_b32 s2, s4, 1
	s_lshl_b32 s62, s2, 7
	s_lshl_b32 s2, s2, 9
	s_mov_b64 s[4:5], 0x8000
	s_waitcnt lgkmcnt(0)
	v_sub_f32_e32 v13, v13, v14
	v_mul_f32_e32 v14, 0x3fb8aa3b, v13
	v_fma_f32 v15, v13, s11, -v14
	v_rndne_f32_e32 v16, v14
	v_fmac_f32_e32 v15, 0x32a5705f, v13
	v_sub_f32_e32 v14, v14, v16
	v_add_f32_e32 v14, v14, v15
	v_exp_f32_e32 v14, v14
	v_cvt_i32_f32_e32 v15, v16
	v_cmp_ngt_f32_e32 vcc, s0, v13
	v_ldexp_f32 v14, v14, v15
	s_nop 0
	v_cndmask_b32_e32 v14, 0, v14, vcc
	v_cmp_nlt_f32_e32 vcc, s1, v13
	s_nop 1
	v_cndmask_b32_e32 v13, v206, v14, vcc
	v_mul_f32_e32 v8, v8, v13
	s_waitcnt vmcnt(3)
	v_mov_b64_e32 v[2:3], v[248:249]
	v_mov_b64_e32 v[4:5], v[250:251]
	v_lshlrev_b32_e32 v13, 16, v2
	v_and_b32_e32 v2, 0xffff0000, v2
	v_mul_f32_e32 v13, v8, v13
	v_mul_f32_e32 v2, v8, v2
	v_cvt_pk_bf16_f32 v13, v13, v1
	ds_write_b16 v164, v13
	v_cvt_pk_bf16_f32 v2, v2, v1
	ds_write_b16 v164, v2 offset:272
	v_lshlrev_b32_e32 v2, 16, v3
	v_mul_f32_e32 v2, v8, v2
	v_cvt_pk_bf16_f32 v2, v2, v1
	ds_write_b16 v164, v2 offset:544
	v_and_b32_e32 v2, 0xffff0000, v3
	v_mul_f32_e32 v2, v8, v2
	v_cvt_pk_bf16_f32 v2, v2, v1
	ds_write_b16 v164, v2 offset:816
	v_lshlrev_b32_e32 v2, 16, v4
	v_mul_f32_e32 v2, v8, v2
	v_cvt_pk_bf16_f32 v2, v2, v1
	ds_write_b16 v164, v2 offset:1088
	v_and_b32_e32 v2, 0xffff0000, v4
	v_mul_f32_e32 v2, v8, v2
	v_cvt_pk_bf16_f32 v2, v2, v1
	ds_write_b16 v164, v2 offset:1360
	v_lshlrev_b32_e32 v2, 16, v5
	v_mul_f32_e32 v2, v8, v2
	v_cvt_pk_bf16_f32 v2, v2, v1
	ds_write_b16 v164, v2 offset:1632
	v_and_b32_e32 v2, 0xffff0000, v5
	v_mul_f32_e32 v2, v8, v2
	v_cvt_pk_bf16_f32 v2, v2, v1
	ds_write_b16 v164, v2 offset:1904
	ds_read_b32 v7, v7
	ds_read_b32 v8, v9 offset:508
	ds_read_b32 v9, v12
	s_waitcnt lgkmcnt(0)
	v_sub_f32_e32 v8, v8, v9
	v_mul_f32_e32 v9, 0x3fb8aa3b, v8
	v_fma_f32 v10, v8, s11, -v9
	v_rndne_f32_e32 v11, v9
	v_fmac_f32_e32 v10, 0x32a5705f, v8
	v_sub_f32_e32 v9, v9, v11
	v_add_f32_e32 v9, v9, v10
	v_exp_f32_e32 v9, v9
	v_cvt_i32_f32_e32 v10, v11
	v_cmp_ngt_f32_e32 vcc, s0, v8
	v_ldexp_f32 v9, v9, v10
	s_nop 0
	v_cndmask_b32_e32 v9, 0, v9, vcc
	v_cmp_nlt_f32_e32 vcc, s1, v8
	s_nop 1
	v_cndmask_b32_e32 v8, v206, v9, vcc
	v_mul_f32_e32 v7, v7, v8
	s_waitcnt vmcnt(2)
; DI float bf2f(unsigned h) { return __uint_as_float(h << 16); }
; DI unsigned short f2bf(float f) { return (unsigned short)(pg8::cvt_pk_bf16(f, 0.f) & 0xffffu); }
; DI void prep_unit(const Params& P, int layer, int b, int c, char* lds, int tid) {
;     ...
;         for (int hs = 0; hs < 2; ++hs) { const int h = 2 * g + hs;
; #pragma unroll
;             for (int i = 0; i < 2; ++i) { const int q = tid + 512 * i, l = q & 127, p0 = (q >> 7) * 8;
;                 const u32x4 v = *(const u32x4*)(SSDB + (size_t)(R0 + l) * 768 + 64 * h + p0);
;                 const float f = dtl[h * CH + l] * expf(acs[h * CH + CH - 1] - acs[h * CH + l]);
;                 bf16_t* d = XT[hs] + p0 * SP + l;
;                 d[0] = f2bf(bf2f(v.x & 0xffffu) * f); d[SP] = f2bf(bf2f(v.x >> 16) * f); d[2 * SP] = f2bf(bf2f(v.y & 0xffffu) * f); d[3 * SP] = f2bf(bf2f(v.y >> 16) * f);
;                 d[4 * SP] = f2bf(bf2f(v.z & 0xffffu) * f); d[5 * SP] = f2bf(bf2f(v.z >> 16) * f); d[6 * SP] = f2bf(bf2f(v.w & 0xffffu) * f); d[7 * SP] = f2bf(bf2f(v.w >> 16) * f); } }
;         __syncthreads();
	v_mov_b64_e32 v[2:3], v[252:253]
	v_mov_b64_e32 v[4:5], v[254:255]
	v_lshlrev_b32_e32 v8, 16, v2
	v_and_b32_e32 v2, 0xffff0000, v2
	v_mul_f32_e32 v8, v7, v8
	v_mul_f32_e32 v2, v7, v2
	v_cvt_pk_bf16_f32 v8, v8, v1
	ds_write_b16 v165, v8
	v_cvt_pk_bf16_f32 v2, v2, v1
	ds_write_b16 v165, v2 offset:272
	v_lshlrev_b32_e32 v2, 16, v3
	v_mul_f32_e32 v2, v7, v2
	v_cvt_pk_bf16_f32 v2, v2, v1
	ds_write_b16 v165, v2 offset:544
	v_and_b32_e32 v2, 0xffff0000, v3
	v_mul_f32_e32 v2, v7, v2
	v_cvt_pk_bf16_f32 v2, v2, v1
	ds_write_b16 v165, v2 offset:816
	v_lshlrev_b32_e32 v2, 16, v4
	v_mul_f32_e32 v2, v7, v2
	v_cvt_pk_bf16_f32 v2, v2, v1
	ds_write_b16 v165, v2 offset:1088
	v_and_b32_e32 v2, 0xffff0000, v4
	v_mul_f32_e32 v2, v7, v2
	v_cvt_pk_bf16_f32 v2, v2, v1
	ds_write_b16 v165, v2 offset:1360
	v_lshlrev_b32_e32 v2, 16, v5
	v_mul_f32_e32 v2, v7, v2
	v_cvt_pk_bf16_f32 v2, v2, v1
	ds_write_b16 v165, v2 offset:1632
	v_and_b32_e32 v2, 0xffff0000, v5
	v_mul_f32_e32 v2, v7, v2
	v_cvt_pk_bf16_f32 v2, v2, v1
	ds_write_b16 v165, v2 offset:1904
	v_lshl_add_u64 v[2:3], v[18:19], 0, s[62:63]
	v_or_b32_e32 v5, s2, v6
	v_lshl_add_u64 v[6:7], v[2:3], 0, v[82:83]
	s_add_i32 s2, s20, s2
	v_add_u32_e32 v4, s19, v5
	v_mov_b32_e32 v6, s2
	v_add_u32_e32 v5, s20, v5
	ds_read_b32 v7, v4
	ds_read_b32 v12, v6 offset:508
	ds_read_b32 v13, v5
	v_lshl_add_u64 v[2:3], v[2:3], 0, v[84:85]
	s_waitcnt lgkmcnt(0)
	v_sub_f32_e32 v12, v12, v13
	v_mul_f32_e32 v13, 0x3fb8aa3b, v12
	v_fma_f32 v14, v12, s11, -v13
	v_rndne_f32_e32 v15, v13
	v_fmac_f32_e32 v14, 0x32a5705f, v12
	v_sub_f32_e32 v13, v13, v15
	v_add_f32_e32 v13, v13, v14
	v_exp_f32_e32 v13, v13
	v_cvt_i32_f32_e32 v14, v15
	v_cmp_ngt_f32_e32 vcc, s0, v12
	v_ldexp_f32 v13, v13, v14
	s_nop 0
	v_cndmask_b32_e32 v13, 0, v13, vcc
	v_cmp_nlt_f32_e32 vcc, s1, v12
	s_nop 1
	v_cndmask_b32_e32 v12, v206, v13, vcc
	v_mul_f32_e32 v7, v7, v12
	s_waitcnt vmcnt(1)
	v_mov_b64_e32 v[8:9], v[90:91]
	v_mov_b64_e32 v[10:11], v[92:93]
	v_lshlrev_b32_e32 v12, 16, v8
	v_and_b32_e32 v8, 0xffff0000, v8
	v_mul_f32_e32 v12, v7, v12
	v_mul_f32_e32 v8, v7, v8
	v_cvt_pk_bf16_f32 v12, v12, v1
	ds_write_b16 v166, v12
	v_cvt_pk_bf16_f32 v8, v8, v1
	ds_write_b16 v166, v8 offset:272
	v_lshlrev_b32_e32 v8, 16, v9
	v_mul_f32_e32 v8, v7, v8
	v_cvt_pk_bf16_f32 v8, v8, v1
	ds_write_b16 v166, v8 offset:544
	v_and_b32_e32 v8, 0xffff0000, v9
	v_mul_f32_e32 v8, v7, v8
	v_cvt_pk_bf16_f32 v8, v8, v1
	ds_write_b16 v166, v8 offset:816
	v_lshlrev_b32_e32 v8, 16, v10
	v_mul_f32_e32 v8, v7, v8
	v_cvt_pk_bf16_f32 v8, v8, v1
	ds_write_b16 v166, v8 offset:1088
	v_and_b32_e32 v8, 0xffff0000, v10
	v_mul_f32_e32 v8, v7, v8
	v_cvt_pk_bf16_f32 v8, v8, v1
	ds_write_b16 v166, v8 offset:1360
	v_lshlrev_b32_e32 v8, 16, v11
	v_mul_f32_e32 v8, v7, v8
	v_cvt_pk_bf16_f32 v8, v8, v1
	ds_write_b16 v166, v8 offset:1632
	v_and_b32_e32 v8, 0xffff0000, v11
	v_mul_f32_e32 v7, v7, v8
	v_cvt_pk_bf16_f32 v7, v7, v1
	ds_write_b16 v166, v7 offset:1904
	ds_read_b32 v2, v4
	ds_read_b32 v3, v6 offset:508
	ds_read_b32 v4, v5
	s_waitcnt lgkmcnt(0)
	v_sub_f32_e32 v3, v3, v4
	v_mul_f32_e32 v4, 0x3fb8aa3b, v3
	v_fma_f32 v5, v3, s11, -v4
	v_rndne_f32_e32 v6, v4
	v_fmac_f32_e32 v5, 0x32a5705f, v3
	v_sub_f32_e32 v4, v4, v6
	v_add_f32_e32 v4, v4, v5
	v_exp_f32_e32 v4, v4
	v_cvt_i32_f32_e32 v5, v6
	v_cmp_ngt_f32_e32 vcc, s0, v3
	v_ldexp_f32 v4, v4, v5
	s_nop 0
	v_cndmask_b32_e32 v4, 0, v4, vcc
	v_cmp_nlt_f32_e32 vcc, s1, v3
	s_nop 1
	v_cndmask_b32_e32 v3, v206, v4, vcc
	v_mul_f32_e32 v2, v2, v3
	s_and_b64 vcc, exec, s[38:39]
	s_mov_b64 s[38:39], 0
	s_waitcnt vmcnt(0)
	v_mov_b64_e32 v[8:9], v[94:95]
	v_mov_b64_e32 v[10:11], v[96:97]
	v_lshlrev_b32_e32 v3, 16, v8
	v_mul_f32_e32 v3, v2, v3
	v_cvt_pk_bf16_f32 v3, v3, v1
	ds_write_b16 v167, v3
	v_and_b32_e32 v3, 0xffff0000, v8
	v_mul_f32_e32 v3, v2, v3
	v_cvt_pk_bf16_f32 v3, v3, v1
	ds_write_b16 v167, v3 offset:272
	v_lshlrev_b32_e32 v3, 16, v9
	v_mul_f32_e32 v3, v2, v3
	v_cvt_pk_bf16_f32 v3, v3, v1
	ds_write_b16 v167, v3 offset:544
	v_and_b32_e32 v3, 0xffff0000, v9
	v_mul_f32_e32 v3, v2, v3
	v_cvt_pk_bf16_f32 v3, v3, v1
	ds_write_b16 v167, v3 offset:816
	v_lshlrev_b32_e32 v3, 16, v10
	v_mul_f32_e32 v3, v2, v3
	v_cvt_pk_bf16_f32 v3, v3, v1
	ds_write_b16 v167, v3 offset:1088
	v_and_b32_e32 v3, 0xffff0000, v10
	v_mul_f32_e32 v3, v2, v3
	v_cvt_pk_bf16_f32 v3, v3, v1
	ds_write_b16 v167, v3 offset:1360
	v_lshlrev_b32_e32 v3, 16, v11
	v_mul_f32_e32 v3, v2, v3
	v_cvt_pk_bf16_f32 v3, v3, v1
	ds_write_b16 v167, v3 offset:1632
	v_and_b32_e32 v3, 0xffff0000, v11
	v_mul_f32_e32 v2, v2, v3
	v_cvt_pk_bf16_f32 v2, v2, v1
	ds_write_b16 v167, v2 offset:1904
	s_waitcnt lgkmcnt(0)
	s_barrier
; DI int crow(int r, int h) { return (r & 3) + 8 * (r >> 2) + 4 * h; }
; #define MFMA32(a, b, c) __builtin_amdgcn_mfma_f32_32x32x16_bf16((a), (b), (c), 0, 0, 0)
; DI void prep_unit(const Params& P, int layer, int b, int c, char* lds, int tid) {
;     ...
;         __syncthreads();
; #pragma unroll
;         for (int hs = 0; hs < 2; ++hs) { const int h = 2 * g + hs;
;             f32x16 acc = {};
; #pragma unroll
;             for (int ks = 0; ks < 8; ++ks) { const bf16x8 a = *(const bf16x8*)(XT[hs] + (32 * pb + r) * SP + 16 * ks + 8 * hh); const bf16x8 bb = *(const bf16x8*)(BT + (32 * nb + r) * SP + 16 * ks + 8 * hh);
;                 acc = MFMA32(a, bb, acc); }
;             float* sp = ST + ((size_t)((b * NCHUNK + c) * 4 + h) * 64) * 128;
; #pragma unroll
;             for (int i = 0; i < 16; ++i) sp[(size_t)(32 * pb + crow(i, hh)) * 128 + 32 * nb + r] = acc[i]; }
;         __syncthreads();
	ds_read_b128 v[2:5], v168
	ds_read_b128 v[86:89], v168 offset:32
	ds_read_b128 v[90:93], v161 offset:34816
	ds_read_b128 v[94:97], v161 offset:34848
	s_waitcnt lgkmcnt(1)
	v_mfma_f32_32x32x16_bf16 v[2:17], v[2:5], v[90:93], 0
	s_waitcnt lgkmcnt(0)
	v_mfma_f32_32x32x16_bf16 v[2:17], v[86:89], v[94:97], v[2:17]
	ds_read_b128 v[86:89], v168 offset:64
	ds_read_b128 v[98:101], v161 offset:34880
	s_waitcnt lgkmcnt(0)
	v_mfma_f32_32x32x16_bf16 v[2:17], v[86:89], v[98:101], v[2:17]
	ds_read_b128 v[86:89], v168 offset:96
	ds_read_b128 v[102:105], v161 offset:34912
	s_waitcnt lgkmcnt(0)
	v_mfma_f32_32x32x16_bf16 v[2:17], v[86:89], v[102:105], v[2:17]
	ds_read_b128 v[86:89], v168 offset:128
	ds_read_b128 v[106:109], v161 offset:34944
	s_waitcnt lgkmcnt(0)
	v_mfma_f32_32x32x16_bf16 v[2:17], v[86:89], v[106:109], v[2:17]
	ds_read_b128 v[86:89], v168 offset:160
	ds_read_b128 v[110:113], v161 offset:34976
	s_waitcnt lgkmcnt(0)
	v_mfma_f32_32x32x16_bf16 v[2:17], v[86:89], v[110:113], v[2:17]
	ds_read_b128 v[86:89], v168 offset:192
	ds_read_b128 v[114:117], v161 offset:35008
	s_waitcnt lgkmcnt(0)
	v_mfma_f32_32x32x16_bf16 v[2:17], v[86:89], v[114:117], v[2:17]
	ds_read_b128 v[86:89], v168 offset:224
	ds_read_b128 v[118:121], v161 offset:35040
	s_waitcnt lgkmcnt(0)
	v_mfma_f32_32x32x16_bf16 v[2:17], v[86:89], v[118:121], v[2:17]
	v_lshlrev_b64 v[86:87], 15, v[122:123]
	v_lshl_add_u64 v[122:123], v[40:41], 0, v[86:87]
	v_lshl_add_u64 v[86:87], v[122:123], 0, v[38:39]
	s_nop 8
	global_store_dword v[86:87], v2, off
	global_store_dword v[86:87], v3, off offset:512
	global_store_dword v[86:87], v4, off offset:1024
	global_store_dword v[86:87], v5, off offset:1536
	v_lshl_add_u64 v[2:3], v[122:123], 0, v[46:47]
	global_store_dword v[2:3], v6, off
	v_lshl_add_u64 v[2:3], v[122:123], 0, v[48:49]
	global_store_dword v[2:3], v7, off
	v_lshl_add_u64 v[2:3], v[122:123], 0, v[50:51]
	global_store_dword v[2:3], v8, off
	v_lshl_add_u64 v[2:3], v[122:123], 0, v[52:53]
	global_store_dword v[2:3], v9, off
	v_lshl_add_u64 v[2:3], v[122:123], 0, v[54:55]
	global_store_dword v[2:3], v10, off
	v_lshl_add_u64 v[2:3], v[122:123], 0, v[56:57]
	global_store_dword v[2:3], v11, off
	v_lshl_add_u64 v[2:3], v[122:123], 0, v[58:59]
	global_store_dword v[2:3], v12, off
	v_lshl_add_u64 v[2:3], v[122:123], 0, v[60:61]
	global_store_dword v[2:3], v13, off
	v_lshl_add_u64 v[2:3], v[122:123], 0, v[62:63]
	global_store_dword v[2:3], v14, off
	v_lshl_add_u64 v[2:3], v[122:123], 0, v[64:65]
	global_store_dword v[2:3], v15, off
	v_lshl_add_u64 v[2:3], v[122:123], 0, v[66:67]
	global_store_dword v[2:3], v16, off
	v_lshl_add_u64 v[2:3], v[122:123], 0, v[68:69]
	global_store_dword v[2:3], v17, off
	ds_read_b128 v[2:5], v169
	ds_read_b128 v[86:89], v169 offset:32
	s_waitcnt lgkmcnt(1)
	v_mfma_f32_32x32x16_bf16 v[2:17], v[2:5], v[90:93], 0
	s_waitcnt lgkmcnt(0)
	v_mfma_f32_32x32x16_bf16 v[2:17], v[86:89], v[94:97], v[2:17]
	ds_read_b128 v[86:89], v169 offset:64
	s_waitcnt lgkmcnt(0)
	v_mfma_f32_32x32x16_bf16 v[2:17], v[86:89], v[98:101], v[2:17]
	ds_read_b128 v[86:89], v169 offset:96
	s_waitcnt lgkmcnt(0)
	v_mfma_f32_32x32x16_bf16 v[2:17], v[86:89], v[102:105], v[2:17]
	ds_read_b128 v[86:89], v169 offset:128
	s_waitcnt lgkmcnt(0)
	v_mfma_f32_32x32x16_bf16 v[2:17], v[86:89], v[106:109], v[2:17]
	ds_read_b128 v[86:89], v169 offset:160
	s_waitcnt lgkmcnt(0)
	v_mfma_f32_32x32x16_bf16 v[2:17], v[86:89], v[110:113], v[2:17]
	ds_read_b128 v[86:89], v169 offset:192
	s_waitcnt lgkmcnt(0)
	v_mfma_f32_32x32x16_bf16 v[2:17], v[86:89], v[114:117], v[2:17]
	ds_read_b128 v[86:89], v169 offset:224
	s_waitcnt lgkmcnt(0)
	v_mfma_f32_32x32x16_bf16 v[2:17], v[86:89], v[118:121], v[2:17]
	v_lshl_add_u64 v[86:87], v[122:123], 0, s[4:5]
	v_lshl_add_u64 v[88:89], v[86:87], 0, v[38:39]
	s_nop 9
	global_store_dword v[88:89], v2, off
	global_store_dword v[88:89], v3, off offset:512
	global_store_dword v[88:89], v4, off offset:1024
	global_store_dword v[88:89], v5, off offset:1536
	v_lshl_add_u64 v[2:3], v[86:87], 0, v[46:47]
	global_store_dword v[2:3], v6, off
	v_lshl_add_u64 v[2:3], v[86:87], 0, v[48:49]
	global_store_dword v[2:3], v7, off
	v_lshl_add_u64 v[2:3], v[86:87], 0, v[50:51]
	global_store_dword v[2:3], v8, off
	v_lshl_add_u64 v[2:3], v[86:87], 0, v[52:53]
	global_store_dword v[2:3], v9, off
	v_lshl_add_u64 v[2:3], v[86:87], 0, v[54:55]
	global_store_dword v[2:3], v10, off
	v_lshl_add_u64 v[2:3], v[86:87], 0, v[56:57]
	global_store_dword v[2:3], v11, off
	v_lshl_add_u64 v[2:3], v[86:87], 0, v[58:59]
	global_store_dword v[2:3], v12, off
	v_lshl_add_u64 v[2:3], v[86:87], 0, v[60:61]
	global_store_dword v[2:3], v13, off
	v_lshl_add_u64 v[2:3], v[86:87], 0, v[62:63]
	global_store_dword v[2:3], v14, off
	v_lshl_add_u64 v[2:3], v[86:87], 0, v[64:65]
	global_store_dword v[2:3], v15, off
	v_lshl_add_u64 v[2:3], v[86:87], 0, v[66:67]
	global_store_dword v[2:3], v16, off
	v_lshl_add_u64 v[2:3], v[86:87], 0, v[68:69]
	s_mov_b32 s5, 1
	global_store_dword v[2:3], v17, off
	s_barrier
	s_cbranch_vccnz .LBB0_201
	s_add_i32 s78, s78, s30
	s_cmpk_gt_i32 s78, 0xff
	s_cbranch_scc0 .LBB0_182

; DI unsigned pk2(float lo, float hi) { return pg8::cvt_pk_bf16(lo, hi); }
; DI int crow(int r, int h) { return (r & 3) + 8 * (r >> 2) + 4 * h; }
; #define MFMA32(a, b, c) __builtin_amdgcn_mfma_f32_32x32x16_bf16((a), (b), (c), 0, 0, 0)
; DI void ssd_out_unit(const Params& P, int layer, int b, int c, char* lds, int tid) {
;     ...
;         for (int sbk = 0; sbk <= lb; ++sbk) {
;             f32x16 X = {};
; #pragma unroll
;             for (int ks = 0; ks < 8; ++ks) { const bf16x8 a = *(const bf16x8*)(BM + (32 * sbk + r) * SP + 16 * ks + 8 * hh); const bf16x8 bb = *(const bf16x8*)(CM + (32 * lb + r) * SP + 16 * ks + 8 * hh);
;                 X = MFMA32(a, bb, X); }
;             f32x16 X0, X1;
; #pragma unroll
;             for (int i = 0; i < 16; ++i) { const int s = 32 * sbk + crow(i, hh); const bool vis = (s <= 32 * lb + r);
;                 X0[i] = vis ? X[i] * __expf(al0 - ac0[s]) : 0.f; X1[i] = vis ? X[i] * __expf(al1 - ac1[s]) : 0.f; }
; #pragma unroll
;             for (int s2 = 0; s2 < 2; ++s2) {
;                 u32x4 pw0, pw1;
;                 pw0.x = pk2(X0[8 * s2], X0[8 * s2 + 1]); pw0.y = pk2(X0[8 * s2 + 2], X0[8 * s2 + 3]); pw0.z = pk2(X0[8 * s2 + 4], X0[8 * s2 + 5]); pw0.w = pk2(X0[8 * s2 + 6], X0[8 * s2 + 7]);
;                 pw1.x = pk2(X1[8 * s2], X1[8 * s2 + 1]); pw1.y = pk2(X1[8 * s2 + 2], X1[8 * s2 + 3]); pw1.z = pk2(X1[8 * s2 + 4], X1[8 * s2 + 5]); pw1.w = pk2(X1[8 * s2 + 6], X1[8 * s2 + 7]);
;                 const int xo = (32 * pb + r) * SP + 32 * sbk + 16 * s2 + 4 * hh;
;                 const u32x2 lo0 = *(const u32x2*)(XT[0] + xo), hi0 = *(const u32x2*)(XT[0] + xo + 8), lo1 = *(const u32x2*)(XT[1] + xo), hi1 = *(const u32x2*)(XT[1] + xo + 8);
;                 u32x4 v0; v0.x = lo0.x; v0.y = lo0.y; v0.z = hi0.x; v0.w = hi0.y; u32x4 v1; v1.x = lo1.x; v1.y = lo1.y; v1.z = hi1.x; v1.w = hi1.y;
;                 y0 = MFMA32(__builtin_bit_cast(bf16x8, pw0), __builtin_bit_cast(bf16x8, v0), y0);
;                 y1 = MFMA32(__builtin_bit_cast(bf16x8, pw1), __builtin_bit_cast(bf16x8, v1), y1); }
.LBB0_371:
	v_add_u32_e32 v49, 0, v137
	v_cvt_pk_bf16_f32 v212, v142, v141
	v_cvt_pk_bf16_f32 v213, v175, v176
	v_cvt_pk_bf16_f32 v214, v177, v190
	v_cvt_pk_bf16_f32 v215, v191, v192
	v_cvt_pk_bf16_f32 v34, v174, v34
	v_cvt_pk_bf16_f32 v35, v35, v36
	v_cvt_pk_bf16_f32 v36, v37, v38
	v_add_u32_e32 v38, 0x11000, v49
	v_cvt_pk_bf16_f32 v37, v39, v193
	v_add_u32_e32 v39, 0x11010, v49
	ds_read_b64 v[174:175], v38
	ds_read_b64 v[176:177], v39
	v_add_u32_e32 v38, 0x15400, v49
	s_waitcnt lgkmcnt(0)
	v_mfma_f32_32x32x16_bf16 v[2:17], v[212:215], v[174:177], v[2:17]
	v_add_u32_e32 v39, 0x15410, v49
	ds_read_b64 v[174:175], v38
	ds_read_b64 v[176:177], v39
	v_add_u32_e32 v140, -1, v140
	v_cmp_eq_u32_e32 vcc, 0, v140
	v_add_u32_e32 v139, 0x2200, v139
	v_add_u32_e32 v138, 32, v138
	v_add_u32_e32 v137, 64, v137
	s_waitcnt lgkmcnt(0)
	v_mfma_f32_32x32x16_bf16 v[18:33], v[34:37], v[174:177], v[18:33]
	v_cvt_pk_bf16_f32 v34, v40, v194
	v_cvt_pk_bf16_f32 v35, v195, v196
	v_cvt_pk_bf16_f32 v36, v197, v198
	v_cvt_pk_bf16_f32 v37, v199, v200
	v_cvt_pk_bf16_f32 v38, v41, v42
	v_cvt_pk_bf16_f32 v39, v43, v44
	v_add_u32_e32 v42, 0x11020, v49
	v_add_u32_e32 v44, 0x11030, v49
	v_cvt_pk_bf16_f32 v40, v45, v46
	v_cvt_pk_bf16_f32 v41, v47, v48
	ds_read_b64 v[42:43], v42
	ds_read_b64 v[44:45], v44
	v_add_u32_e32 v46, 0x15420, v49
	s_waitcnt lgkmcnt(0)
	v_mfma_f32_32x32x16_bf16 v[2:17], v[34:37], v[42:45], v[2:17]
	v_add_u32_e32 v36, 0x15430, v49
	ds_read_b64 v[34:35], v46
	ds_read_b64 v[36:37], v36
	s_or_b64 s[58:59], vcc, s[58:59]
	v_add_u32_e32 v136, 0x80, v136
	s_waitcnt lgkmcnt(0)
	v_mfma_f32_32x32x16_bf16 v[18:33], v[38:41], v[34:37], v[18:33]
	s_andn2_b64 exec, exec, s[58:59]
	s_cbranch_execz .LBB0_367
.LBB0_372:
	v_add_u32_e32 v236, 0, v136
	v_add_u32_e32 v236, 0x22020, v236
	ds_read_b128 v[216:219], v236
	ds_read_b128 v[220:223], v236 offset:32
	ds_read_b128 v[224:227], v236 offset:64
	ds_read_b128 v[228:231], v236 offset:96
	ds_read_b128 v[232:235], v236 offset:512
	ds_read_b128 v[244:247], v236 offset:544
	ds_read_b128 v[248:251], v236 offset:576
	ds_read_b128 v[252:255], v236 offset:608
	v_add_u32_e32 v141, 0, v139
	ds_read_b128 v[34:37], v141
	ds_read_b128 v[38:41], v151
	ds_read_b128 v[174:177], v141 offset:32
	ds_read_b128 v[190:193], v151 offset:32
	v_add_u32_e32 v143, 0, v136
	v_mov_b32_e32 v142, 0
	s_waitcnt lgkmcnt(2)
	v_mfma_f32_32x32x16_bf16 v[34:49], v[34:37], v[38:41], 0
	s_waitcnt lgkmcnt(0)
	v_mfma_f32_32x32x16_bf16 v[34:49], v[174:177], v[190:193], v[34:49]
	ds_read_b128 v[174:177], v141 offset:64
	ds_read_b128 v[190:193], v151 offset:64
	s_waitcnt lgkmcnt(0)
	v_mfma_f32_32x32x16_bf16 v[34:49], v[174:177], v[190:193], v[34:49]
	ds_read_b128 v[174:177], v141 offset:96
	ds_read_b128 v[190:193], v151 offset:96
	s_waitcnt lgkmcnt(0)
	v_mfma_f32_32x32x16_bf16 v[34:49], v[174:177], v[190:193], v[34:49]
	ds_read_b128 v[174:177], v141 offset:128
	ds_read_b128 v[190:193], v151 offset:128
	s_waitcnt lgkmcnt(0)
	v_mfma_f32_32x32x16_bf16 v[34:49], v[174:177], v[190:193], v[34:49]
	ds_read_b128 v[174:177], v141 offset:160
	ds_read_b128 v[190:193], v151 offset:160
	s_waitcnt lgkmcnt(0)
	v_mfma_f32_32x32x16_bf16 v[34:49], v[174:177], v[190:193], v[34:49]
	ds_read_b128 v[174:177], v141 offset:192
	ds_read_b128 v[190:193], v151 offset:192
	s_waitcnt lgkmcnt(0)
	v_mfma_f32_32x32x16_bf16 v[34:49], v[174:177], v[190:193], v[34:49]
	ds_read_b128 v[174:177], v141 offset:224
	ds_read_b128 v[190:193], v151 offset:224
	v_mov_b32_e32 v141, 0
	s_waitcnt lgkmcnt(0)
	v_mfma_f32_32x32x16_bf16 v[34:49], v[174:177], v[190:193], v[34:49]
	s_waitcnt lgkmcnt(0)
; DI int crow(int r, int h) { return (r & 3) + 8 * (r >> 2) + 4 * h; }
; DI void ssd_out_unit(const Params& P, int layer, int b, int c, char* lds, int tid) {
;     ...
;             f32x16 X0, X1;
; #pragma unroll
;             for (int i = 0; i < 16; ++i) { const int s = 32 * sbk + crow(i, hh); const bool vis = (s <= 32 * lb + r);
;                 X0[i] = vis ? X[i] * __expf(al0 - ac0[s]) : 0.f; X1[i] = vis ? X[i] * __expf(al1 - ac1[s]) : 0.f; }
	v_sub_u32_e32 v237, v149, v138
	v_add_u32_e32 v237, 27, v237
	v_sub_f32_e32 v216, v134, v216
	v_sub_f32_e32 v232, v135, v232
	v_sub_f32_e32 v217, v134, v217
	v_sub_f32_e32 v233, v135, v233
	v_sub_f32_e32 v218, v134, v218
	v_sub_f32_e32 v234, v135, v234
	v_sub_f32_e32 v219, v134, v219
	v_sub_f32_e32 v235, v135, v235
	v_sub_f32_e32 v220, v134, v220
	v_sub_f32_e32 v244, v135, v244
	v_sub_f32_e32 v221, v134, v221
	v_sub_f32_e32 v245, v135, v245
	v_sub_f32_e32 v222, v134, v222
	v_sub_f32_e32 v246, v135, v246
	v_sub_f32_e32 v223, v134, v223
	v_sub_f32_e32 v247, v135, v247
	v_sub_f32_e32 v224, v134, v224
	v_sub_f32_e32 v248, v135, v248
	v_sub_f32_e32 v225, v134, v225
	v_sub_f32_e32 v249, v135, v249
	v_sub_f32_e32 v226, v134, v226
	v_sub_f32_e32 v250, v135, v250
	v_sub_f32_e32 v227, v134, v227
	v_sub_f32_e32 v251, v135, v251
	v_sub_f32_e32 v228, v134, v228
	v_sub_f32_e32 v252, v135, v252
	v_sub_f32_e32 v229, v134, v229
	v_sub_f32_e32 v253, v135, v253
	v_sub_f32_e32 v230, v134, v230
	v_sub_f32_e32 v254, v135, v254
	v_sub_f32_e32 v231, v134, v231
	v_sub_f32_e32 v255, v135, v255
	v_mul_f32_e32 v216, 0x3fb8aa3b, v216
	v_mul_f32_e32 v232, 0x3fb8aa3b, v232
	v_mul_f32_e32 v217, 0x3fb8aa3b, v217
	v_mul_f32_e32 v233, 0x3fb8aa3b, v233
	v_mul_f32_e32 v218, 0x3fb8aa3b, v218
	v_mul_f32_e32 v234, 0x3fb8aa3b, v234
	v_mul_f32_e32 v219, 0x3fb8aa3b, v219
	v_mul_f32_e32 v235, 0x3fb8aa3b, v235
	v_mul_f32_e32 v220, 0x3fb8aa3b, v220
	v_mul_f32_e32 v244, 0x3fb8aa3b, v244
	v_mul_f32_e32 v221, 0x3fb8aa3b, v221
	v_mul_f32_e32 v245, 0x3fb8aa3b, v245
	v_mul_f32_e32 v222, 0x3fb8aa3b, v222
	v_mul_f32_e32 v246, 0x3fb8aa3b, v246
	v_mul_f32_e32 v223, 0x3fb8aa3b, v223
	v_mul_f32_e32 v247, 0x3fb8aa3b, v247
	v_mul_f32_e32 v224, 0x3fb8aa3b, v224
	v_mul_f32_e32 v248, 0x3fb8aa3b, v248
	v_mul_f32_e32 v225, 0x3fb8aa3b, v225
	v_mul_f32_e32 v249, 0x3fb8aa3b, v249
	v_mul_f32_e32 v226, 0x3fb8aa3b, v226
	v_mul_f32_e32 v250, 0x3fb8aa3b, v250
	v_mul_f32_e32 v227, 0x3fb8aa3b, v227
	v_mul_f32_e32 v251, 0x3fb8aa3b, v251
	v_mul_f32_e32 v228, 0x3fb8aa3b, v228
	v_mul_f32_e32 v252, 0x3fb8aa3b, v252
	v_mul_f32_e32 v229, 0x3fb8aa3b, v229
	v_mul_f32_e32 v253, 0x3fb8aa3b, v253
	v_mul_f32_e32 v230, 0x3fb8aa3b, v230
	v_mul_f32_e32 v254, 0x3fb8aa3b, v254
	v_mul_f32_e32 v231, 0x3fb8aa3b, v231
	v_mul_f32_e32 v255, 0x3fb8aa3b, v255
	v_exp_f32_e32 v216, v216
	v_exp_f32_e32 v232, v232
	v_exp_f32_e32 v217, v217
	v_exp_f32_e32 v233, v233
	v_exp_f32_e32 v218, v218
	v_exp_f32_e32 v234, v234
	v_exp_f32_e32 v219, v219
	v_exp_f32_e32 v235, v235
	v_exp_f32_e32 v220, v220
	v_exp_f32_e32 v244, v244
	v_exp_f32_e32 v221, v221
	v_exp_f32_e32 v245, v245
	v_exp_f32_e32 v222, v222
	v_exp_f32_e32 v246, v246
	v_exp_f32_e32 v223, v223
	v_exp_f32_e32 v247, v247
	v_exp_f32_e32 v224, v224
	v_exp_f32_e32 v248, v248
	v_exp_f32_e32 v225, v225
	v_exp_f32_e32 v249, v249
	v_exp_f32_e32 v226, v226
	v_exp_f32_e32 v250, v250
	v_exp_f32_e32 v227, v227
	v_exp_f32_e32 v251, v251
	v_exp_f32_e32 v228, v228
	v_exp_f32_e32 v252, v252
	v_exp_f32_e32 v229, v229
	v_exp_f32_e32 v253, v253
	v_exp_f32_e32 v230, v230
	v_exp_f32_e32 v254, v254
	v_exp_f32_e32 v231, v231
	v_exp_f32_e32 v255, v255
	s_nop 0
	v_mul_f32_e32 v216, v34, v216
	v_mul_f32_e32 v232, v34, v232
	v_mul_f32_e32 v217, v35, v217
	v_mul_f32_e32 v233, v35, v233
	v_mul_f32_e32 v218, v36, v218
	v_mul_f32_e32 v234, v36, v234
	v_mul_f32_e32 v219, v37, v219
	v_mul_f32_e32 v235, v37, v235
	v_mul_f32_e32 v220, v38, v220
	v_mul_f32_e32 v244, v38, v244
	v_mul_f32_e32 v221, v39, v221
	v_mul_f32_e32 v245, v39, v245
	v_mul_f32_e32 v222, v40, v222
	v_mul_f32_e32 v246, v40, v246
	v_mul_f32_e32 v223, v41, v223
	v_mul_f32_e32 v247, v41, v247
	v_mul_f32_e32 v224, v42, v224
	v_mul_f32_e32 v248, v42, v248
	v_mul_f32_e32 v225, v43, v225
	v_mul_f32_e32 v249, v43, v249
	v_mul_f32_e32 v226, v44, v226
	v_mul_f32_e32 v250, v44, v250
	v_mul_f32_e32 v227, v45, v227
	v_mul_f32_e32 v251, v45, v251
	v_mul_f32_e32 v228, v46, v228
	v_mul_f32_e32 v252, v46, v252
	v_mul_f32_e32 v229, v47, v229
	v_mul_f32_e32 v253, v47, v253
	v_mul_f32_e32 v230, v48, v230
	v_mul_f32_e32 v254, v48, v254
	v_mul_f32_e32 v231, v49, v231
	v_mul_f32_e32 v255, v49, v255
	v_cmp_le_i32_e32 vcc, 0, v237
	s_nop 1
	v_cndmask_b32_e32 v142, 0, v216, vcc
	v_cndmask_b32_e32 v174, 0, v232, vcc
	v_cmp_le_i32_e32 vcc, 1, v237
	s_nop 1
	v_cndmask_b32_e32 v141, 0, v217, vcc
	v_cndmask_b32_e32 v34, 0, v233, vcc
	v_cmp_le_i32_e32 vcc, 2, v237
	s_nop 1
	v_cndmask_b32_e32 v175, 0, v218, vcc
	v_cndmask_b32_e32 v35, 0, v234, vcc
	v_cmp_le_i32_e32 vcc, 3, v237
	s_nop 1
	v_cndmask_b32_e32 v176, 0, v219, vcc
	v_cndmask_b32_e32 v36, 0, v235, vcc
	v_cmp_le_i32_e32 vcc, 8, v237
	s_nop 1
	v_cndmask_b32_e32 v177, 0, v220, vcc
	v_cndmask_b32_e32 v37, 0, v244, vcc
	v_cmp_le_i32_e32 vcc, 9, v237
	s_nop 1
	v_cndmask_b32_e32 v190, 0, v221, vcc
	v_cndmask_b32_e32 v38, 0, v245, vcc
	v_cmp_le_i32_e32 vcc, 10, v237
	s_nop 1
	v_cndmask_b32_e32 v191, 0, v222, vcc
	v_cndmask_b32_e32 v39, 0, v246, vcc
	v_cmp_le_i32_e32 vcc, 11, v237
	s_nop 1
	v_cndmask_b32_e32 v192, 0, v223, vcc
	v_cndmask_b32_e32 v193, 0, v247, vcc
	v_cmp_le_i32_e32 vcc, 16, v237
	s_nop 1
	v_cndmask_b32_e32 v40, 0, v224, vcc
	v_cndmask_b32_e32 v41, 0, v248, vcc
	v_cmp_le_i32_e32 vcc, 17, v237
	s_nop 1
	v_cndmask_b32_e32 v194, 0, v225, vcc
	v_cndmask_b32_e32 v42, 0, v249, vcc
	v_cmp_le_i32_e32 vcc, 18, v237
	s_nop 1
	v_cndmask_b32_e32 v195, 0, v226, vcc
	v_cndmask_b32_e32 v43, 0, v250, vcc
	v_cmp_le_i32_e32 vcc, 19, v237
	s_nop 1
	v_cndmask_b32_e32 v196, 0, v227, vcc
	v_cndmask_b32_e32 v44, 0, v251, vcc
	v_cmp_le_i32_e32 vcc, 24, v237
	s_nop 1
	v_cndmask_b32_e32 v197, 0, v228, vcc
	v_cndmask_b32_e32 v45, 0, v252, vcc
	v_cmp_le_i32_e32 vcc, 25, v237
	s_nop 1
	v_cndmask_b32_e32 v198, 0, v229, vcc
	v_cndmask_b32_e32 v46, 0, v253, vcc
	v_cmp_le_i32_e32 vcc, 26, v237
	s_nop 1
	v_cndmask_b32_e32 v199, 0, v230, vcc
	v_cndmask_b32_e32 v47, 0, v254, vcc
	v_cmp_le_i32_e32 vcc, 27, v237
	s_nop 1
	v_cndmask_b32_e32 v200, 0, v231, vcc
	v_cndmask_b32_e32 v48, 0, v255, vcc
	s_branch .LBB0_371
